# NA context items reassigned two each to the 16 workgroups that own the short boundary-row items (removes most of the 32-workgroup tail)
# speedup vs baseline: 1.0066x; 1.0016x over previous
; __device__ __forceinline__ int item_of(int it, int nmain, int ntotal) {
;     const int bid = blockIdx.x, G = gridDim.x;
;     if (G == 256 && nmain == 1024) { if (it < 4) return 128 * (bid & 7) + 32 * it + (bid >> 3); const int e = nmain + (it - 4) * 256 + bid; return e < ntotal ? e : -1; }
;     const int e = bid + it * G; return e < ntotal ? e : -1;
; }
.LBB0_364:
	s_andn2_b64 vcc, exec, s[0:1]
	s_cbranch_vccnz .LBB0_369
	s_cmp_gt_u32 s92, 3
	s_mov_b64 s[0:1], -1
	s_cbranch_scc0 .LBB0_367
	v_readlane_b32 s1, v240, 33
	s_add_i32 s0, s1, 0xffffff10
	s_cmp_lt_u32 s1, 8
	s_cselect_b32 s0, s1, s0
	s_cselect_b32 s7, 1, 0
	s_cmp_gt_u32 s1, 0xf7
	s_cselect_b32 s7, 1, s7
	s_lshl_b32 s6, s92, 4
	s_add_i32 s0, s0, s6
	s_add_i32 s0, s0, 0x3c0
	s_cmp_lt_u32 s92, 6
	s_cselect_b32 s7, s7, 0
	s_cmp_lg_u32 s7, 0
	s_cselect_b32 s7, s0, -1
	s_mov_b64 s[0:1], 0
